# row passes: wave sums fully off the LDS crossbar (DPP for in-row hops, v_readlane row sums added as (R0+R1)+(R2+R3) for cross-row hops)
# speedup vs baseline: 1.0123x; 1.0123x over previous
.LBB0_562:
	s_lshl_b32 s6, s24, 3
	s_ashr_i32 s7, s6, 31
	v_lshlrev_b32_e32 v49, 2, v116
	s_lshl_b64 s[10:11], s[6:7], 10
	v_mov_b32_e32 v217, s11
	v_or_b32_e32 v216, s10, v49
	v_lshlrev_b64 v[66:67], 1, v[216:217]
	v_lshl_add_u64 v[218:219], s[8:9], 0, v[66:67]
	v_lshl_add_u64 v[66:67], s[38:39], 0, v[66:67]
	global_load_dwordx2 v[90:91], v[218:219], off
	global_load_dwordx2 v[224:225], v[218:219], off offset:512
	global_load_dwordx2 v[222:223], v[218:219], off offset:1024
	global_load_dwordx2 v[220:221], v[218:219], off offset:1536
	global_load_dwordx2 v[86:87], v[66:67], off
	global_load_dwordx2 v[88:89], v[66:67], off offset:512
	global_load_dwordx2 v[92:93], v[66:67], off offset:1024
	global_load_dwordx2 v[230:231], v[66:67], off offset:1536
	s_or_b32 s10, s6, 1
	s_ashr_i32 s11, s10, 31
	s_lshl_b64 s[10:11], s[10:11], 10
	v_or_b32_e32 v196, s10, v49
	s_or_b32 s10, s6, 2
	v_mov_b32_e32 v197, s11
	s_ashr_i32 s11, s10, 31
	s_lshl_b64 s[10:11], s[10:11], 10
	v_or_b32_e32 v176, s10, v49
	s_or_b32 s10, s6, 3
	v_mov_b32_e32 v177, s11
	s_ashr_i32 s11, s10, 31
	s_lshl_b64 s[10:11], s[10:11], 10
	v_lshlrev_b64 v[66:67], 1, v[196:197]
	v_or_b32_e32 v156, s10, v49
	s_or_b32 s10, s6, 4
	v_lshl_add_u64 v[198:199], s[8:9], 0, v[66:67]
	v_lshl_add_u64 v[66:67], s[38:39], 0, v[66:67]
	v_mov_b32_e32 v157, s11
	s_ashr_i32 s11, s10, 31
	global_load_dwordx2 v[206:207], v[198:199], off
	global_load_dwordx2 v[204:205], v[198:199], off offset:512
	global_load_dwordx2 v[202:203], v[198:199], off offset:1024
	global_load_dwordx2 v[200:201], v[198:199], off offset:1536
	global_load_dwordx2 v[214:215], v[66:67], off
	global_load_dwordx2 v[212:213], v[66:67], off offset:512
	global_load_dwordx2 v[210:211], v[66:67], off offset:1024
	global_load_dwordx2 v[208:209], v[66:67], off offset:1536
	v_lshlrev_b64 v[66:67], 1, v[176:177]
	s_lshl_b64 s[10:11], s[10:11], 10
	v_lshl_add_u64 v[178:179], s[8:9], 0, v[66:67]
	v_lshl_add_u64 v[66:67], s[38:39], 0, v[66:67]
	v_or_b32_e32 v134, s10, v49
	s_or_b32 s10, s6, 5
	global_load_dwordx2 v[186:187], v[178:179], off
	global_load_dwordx2 v[184:185], v[178:179], off offset:512
	global_load_dwordx2 v[182:183], v[178:179], off offset:1024
	global_load_dwordx2 v[180:181], v[178:179], off offset:1536
	global_load_dwordx2 v[194:195], v[66:67], off
	global_load_dwordx2 v[192:193], v[66:67], off offset:512
	global_load_dwordx2 v[190:191], v[66:67], off offset:1024
	global_load_dwordx2 v[188:189], v[66:67], off offset:1536
	v_lshlrev_b64 v[66:67], 1, v[156:157]
	v_mov_b32_e32 v135, s11
	s_ashr_i32 s11, s10, 31
	v_lshl_add_u64 v[158:159], s[8:9], 0, v[66:67]
	v_lshl_add_u64 v[66:67], s[38:39], 0, v[66:67]
	s_lshl_b64 s[10:11], s[10:11], 10
	global_load_dwordx2 v[166:167], v[158:159], off
	global_load_dwordx2 v[164:165], v[158:159], off offset:512
	global_load_dwordx2 v[162:163], v[158:159], off offset:1024
	global_load_dwordx2 v[160:161], v[158:159], off offset:1536
	global_load_dwordx2 v[174:175], v[66:67], off
	global_load_dwordx2 v[172:173], v[66:67], off offset:512
	global_load_dwordx2 v[170:171], v[66:67], off offset:1024
	global_load_dwordx2 v[168:169], v[66:67], off offset:1536
	v_lshlrev_b64 v[66:67], 1, v[134:135]
	v_or_b32_e32 v114, s10, v49
	s_or_b32 s10, s6, 6
	v_lshl_add_u64 v[136:137], s[8:9], 0, v[66:67]
	v_lshl_add_u64 v[66:67], s[38:39], 0, v[66:67]
	v_mov_b32_e32 v115, s11
	s_ashr_i32 s11, s10, 31
	global_load_dwordx2 v[146:147], v[136:137], off
	global_load_dwordx2 v[142:143], v[136:137], off offset:512
	global_load_dwordx2 v[140:141], v[136:137], off offset:1024
	global_load_dwordx2 v[138:139], v[136:137], off offset:1536
	global_load_dwordx2 v[154:155], v[66:67], off
	global_load_dwordx2 v[152:153], v[66:67], off offset:512
	global_load_dwordx2 v[150:151], v[66:67], off offset:1024
	global_load_dwordx2 v[148:149], v[66:67], off offset:1536
	v_lshlrev_b64 v[66:67], 1, v[114:115]
	s_lshl_b64 s[10:11], s[10:11], 10
	v_lshl_add_u64 v[116:117], s[8:9], 0, v[66:67]
	v_lshl_add_u64 v[66:67], s[38:39], 0, v[66:67]
	v_mov_b32_e32 v95, s11
	v_or_b32_e32 v94, s10, v49
	s_or_b32 s6, s6, 7
	global_load_dwordx2 v[124:125], v[116:117], off
	global_load_dwordx2 v[122:123], v[116:117], off offset:512
	global_load_dwordx2 v[120:121], v[116:117], off offset:1024
	global_load_dwordx2 v[118:119], v[116:117], off offset:1536
	global_load_dwordx2 v[132:133], v[66:67], off
	global_load_dwordx2 v[130:131], v[66:67], off offset:512
	global_load_dwordx2 v[128:129], v[66:67], off offset:1024
	global_load_dwordx2 v[126:127], v[66:67], off offset:1536
	v_lshlrev_b64 v[66:67], 1, v[94:95]
	s_ashr_i32 s7, s6, 31
	v_lshl_add_u64 v[96:97], s[8:9], 0, v[66:67]
	v_lshl_add_u64 v[66:67], s[38:39], 0, v[66:67]
	s_lshl_b64 s[6:7], s[6:7], 10
	global_load_dwordx2 v[104:105], v[96:97], off
	global_load_dwordx2 v[102:103], v[96:97], off offset:512
	global_load_dwordx2 v[100:101], v[96:97], off offset:1024
	global_load_dwordx2 v[98:99], v[96:97], off offset:1536
	global_load_dwordx2 v[112:113], v[66:67], off
	global_load_dwordx2 v[110:111], v[66:67], off offset:512
	global_load_dwordx2 v[108:109], v[66:67], off offset:1024
	global_load_dwordx2 v[106:107], v[66:67], off offset:1536
	v_mov_b32_e32 v67, s7
	v_or_b32_e32 v66, s6, v49
	v_lshlrev_b64 v[70:71], 1, v[66:67]
	v_lshl_add_u64 v[68:69], s[8:9], 0, v[70:71]
	v_lshl_add_u64 v[78:79], s[38:39], 0, v[70:71]
	global_load_dwordx2 v[76:77], v[68:69], off
	global_load_dwordx2 v[74:75], v[68:69], off offset:512
	global_load_dwordx2 v[72:73], v[68:69], off offset:1024
	global_load_dwordx2 v[70:71], v[68:69], off offset:1536
	global_load_dwordx2 v[84:85], v[78:79], off
	global_load_dwordx2 v[82:83], v[78:79], off offset:512
	global_load_dwordx2 v[80:81], v[78:79], off offset:1024
	s_nop 0
	global_load_dwordx2 v[78:79], v[78:79], off offset:1536
	v_xor_b32_e32 v144, 4, v49
	v_xor_b32_e32 v251, 32, v49
	v_xor_b32_e32 v252, 64, v49
	s_waitcnt vmcnt(0)
	v_pk_add_f32 v[20:21], v[20:21], 1.0 op_sel_hi:[1,0]
	v_pk_add_f32 v[22:23], v[22:23], 1.0 op_sel_hi:[1,0]
	v_pk_mul_f32 v[20:21], v[48:49], v[20:21] op_sel_hi:[0,1]
	v_pk_mul_f32 v[22:23], v[48:49], v[22:23] op_sel_hi:[0,1]
	s_cmp_lg_u64 s[0:1], 0
	s_cselect_b64 s[8:9], -1, 0
	s_cmp_eq_u64 s[0:1], 0
	v_and_b32_e32 v237, 0xffff0000, v86
	v_and_b32_e32 v249, 0xffff0000, v87
	v_lshlrev_b32_e32 v236, 16, v86
	v_lshlrev_b32_e32 v248, 16, v87
	v_mul_f32_e32 v86, v249, v249
	v_and_b32_e32 v243, 0xffff0000, v89
	v_and_b32_e32 v242, 0xffff0000, v88
	v_lshlrev_b32_e32 v232, 16, v92
	v_and_b32_e32 v233, 0xffff0000, v92
	v_mul_f32_e32 v92, v237, v237
	v_pk_fma_f32 v[86:87], v[248:249], v[248:249], v[86:87] op_sel_hi:[1,1,0]
	v_lshlrev_b32_e32 v241, 16, v89
	v_lshlrev_b32_e32 v240, 16, v88
	v_pk_mul_f32 v[88:89], v[242:243], v[242:243]
	v_lshlrev_b32_e32 v234, 16, v93
	v_and_b32_e32 v235, 0xffff0000, v93
	v_lshlrev_b32_e32 v229, 16, v230
	v_pk_fma_f32 v[92:93], v[236:237], v[236:237], v[92:93] op_sel_hi:[1,1,0]
	v_pk_fma_f32 v[88:89], v[240:241], v[240:241], v[88:89]
	v_and_b32_e32 v227, 0xffff0000, v230
	v_mov_b32_e32 v228, v92
	v_mov_b32_e32 v238, v86
	v_mov_b32_e32 v239, v229
	v_mul_f32_e32 v226, v227, v227
	v_pk_add_f32 v[86:87], v[92:93], v[86:87]
	v_pk_mul_f32 v[92:93], v[228:229], v[238:239]
	v_pk_add_f32 v[88:89], v[88:89], v[88:89] op_sel:[0,1] op_sel_hi:[1,0]
	v_mov_b32_e32 v87, v93
	v_mov_b32_e32 v89, v226
	v_lshlrev_b32_e32 v230, 16, v231
	v_and_b32_e32 v231, 0xffff0000, v231
	v_pk_add_f32 v[86:87], v[86:87], v[88:89]
	v_mul_f32_e32 v88, v233, v233
	v_mul_f32_e32 v92, v235, v235
	v_mul_f32_e32 v246, v230, v230
	v_mul_f32_e32 v250, v231, v231
	v_pk_fma_f32 v[88:89], v[232:233], v[232:233], v[88:89] op_sel_hi:[1,1,0]
	v_pk_fma_f32 v[92:93], v[234:235], v[234:235], v[92:93] op_sel_hi:[1,1,0]
	v_mov_b32_e32 v89, v246
	v_mov_b32_e32 v93, v250
	v_pk_add_f32 v[88:89], v[88:89], v[92:93]
	v_xor_b32_e32 v228, 8, v49
	v_pk_add_f32 v[86:87], v[86:87], v[88:89]
	v_xor_b32_e32 v250, 16, v49
	v_add_f32_e32 v86, v86, v87
	s_nop 1
	v_mov_b32_dpp v87, v86 quad_perm:[1,0,3,2] row_mask:0xf bank_mask:0xf
	v_xor_b32_e32 v246, 0x80, v49
	v_pk_mul_f32 v[88:89], v[18:19], v[22:23]
	v_and_b32_e32 v19, 0xffff0000, v91
	s_waitcnt lgkmcnt(0)
	v_add_f32_e32 v86, v86, v87
	s_nop 1
	v_mov_b32_dpp v87, v86 quad_perm:[2,3,0,1] row_mask:0xf bank_mask:0xf
	s_waitcnt lgkmcnt(0)
	v_add_f32_e32 v86, v86, v87
	s_nop 1
	v_mov_b32_dpp v87, v86 row_half_mirror row_mask:0xf bank_mask:0xf
	s_waitcnt lgkmcnt(0)
	v_add_f32_e32 v86, v86, v87
	s_nop 1
	v_mov_b32_dpp v87, v86 row_mirror row_mask:0xf bank_mask:0xf
	s_waitcnt lgkmcnt(0)
	v_add_f32_e32 v92, v86, v87
	v_pk_mul_f32 v[86:87], v[16:17], v[20:21]
	v_lshlrev_b32_e32 v16, 16, v90
	s_waitcnt lgkmcnt(0)
	s_nop 0
	v_readlane_b32 s98, v92, 32
	v_readlane_b32 s100, v92, 48
	s_nop 1
	v_mov_b32_e32 v93, s100
	v_add_f32_e32 v93, s98, v93
	v_readlane_b32 s98, v92, 0
	v_readlane_b32 s100, v92, 16
	s_nop 1
	v_mov_b32_e32 v17, s100
	v_add_f32_e32 v17, s98, v17
	v_add_f32_e32 v17, v17, v93
	s_waitcnt lgkmcnt(0)
	v_fmamk_f32 v17, v17, 0x3a800000, v247
	v_mul_f32_e32 v18, 0x4b800000, v17
	v_cmp_gt_f32_e32 vcc, s35, v17
	s_nop 1
	v_cndmask_b32_e32 v17, v17, v18, vcc
	v_rsq_f32_e32 v20, v17
	v_and_b32_e32 v17, 0xffff0000, v90
	v_lshlrev_b32_e32 v18, 16, v91
	v_mul_f32_e32 v21, 0x45800000, v20
	v_cndmask_b32_e32 v238, v20, v21, vcc
	v_pk_mul_f32 v[20:21], v[238:239], v[236:237] op_sel_hi:[0,1]
	v_pk_mul_f32 v[22:23], v[238:239], v[248:249] op_sel_hi:[0,1]
	v_pk_fma_f32 v[18:19], v[88:89], v[22:23], v[18:19]
	v_pk_fma_f32 v[16:17], v[86:87], v[20:21], v[16:17]
	v_lshl_add_u64 v[236:237], v[216:217], 2, s[0:1]
	s_cbranch_scc1 .LBB0_573
	global_store_dwordx4 v[236:237], v[16:19], off
	s_cbranch_execnz .LBB0_565

.LBB0_579:
	s_and_b64 vcc, exec, s[4:5]
	s_cbranch_vccnz .LBB0_581
	v_mul_f32_e32 v40, v17, v17
	v_mul_f32_e32 v41, v19, v19
	v_fmac_f32_e32 v40, v16, v16
	v_fmac_f32_e32 v41, v18, v18
	v_add_f32_e32 v40, v40, v41
	v_mul_f32_e32 v41, v21, v21
	v_mul_f32_e32 v42, v23, v23
	v_fmac_f32_e32 v41, v20, v20
	v_fmac_f32_e32 v42, v22, v22
	v_add_f32_e32 v41, v41, v42
	v_add_f32_e32 v40, v40, v41
	v_mul_f32_e32 v41, v25, v25
	v_mul_f32_e32 v42, v27, v27
	v_fmac_f32_e32 v41, v24, v24
	v_fmac_f32_e32 v42, v26, v26
	v_add_f32_e32 v41, v41, v42
	v_add_f32_e32 v40, v41, v40
	v_mul_f32_e32 v41, v29, v29
	v_mul_f32_e32 v42, v31, v31
	v_fmac_f32_e32 v41, v28, v28
	v_fmac_f32_e32 v42, v30, v30
	v_add_f32_e32 v41, v41, v42
	v_add_f32_e32 v40, v41, v40
	s_nop 1
	v_mov_b32_dpp v41, v40 quad_perm:[1,0,3,2] row_mask:0xf bank_mask:0xf
	s_waitcnt lgkmcnt(0)
	v_add_f32_e32 v40, v40, v41
	s_nop 1
	v_mov_b32_dpp v41, v40 quad_perm:[2,3,0,1] row_mask:0xf bank_mask:0xf
	s_waitcnt lgkmcnt(0)
	v_add_f32_e32 v40, v40, v41
	s_nop 1
	v_mov_b32_dpp v41, v40 row_half_mirror row_mask:0xf bank_mask:0xf
	s_waitcnt lgkmcnt(0)
	v_add_f32_e32 v40, v40, v41
	s_nop 1
	v_mov_b32_dpp v41, v40 row_mirror row_mask:0xf bank_mask:0xf
	s_waitcnt lgkmcnt(0)
	v_add_f32_e32 v40, v40, v41
	s_waitcnt lgkmcnt(0)
	s_nop 0
	v_readlane_b32 s98, v40, 32
	v_readlane_b32 s100, v40, 48
	s_nop 1
	v_mov_b32_e32 v41, s100
	v_add_f32_e32 v41, s98, v41
	v_readlane_b32 s98, v40, 0
	v_readlane_b32 s100, v40, 16
	s_nop 1
	v_mov_b32_e32 v40, s100
	v_add_f32_e32 v40, s98, v40
	v_add_f32_e32 v40, v40, v41
	s_waitcnt lgkmcnt(0)
	v_fmamk_f32 v40, v40, 0x3a800000, v247
	v_mul_f32_e32 v41, 0x4b800000, v40
	v_cmp_gt_f32_e32 vcc, s35, v40
	s_nop 1
	v_cndmask_b32_e32 v40, v40, v41, vcc
	v_rsq_f32_e32 v42, v40
	v_lshl_add_u64 v[40:41], v[216:217], 1, s[42:43]
	v_mul_f32_e32 v43, 0x45800000, v42
	v_cndmask_b32_e32 v42, v42, v43, vcc
	v_pk_mul_f32 v[16:17], v[16:17], v[42:43] op_sel_hi:[1,0]
	v_pk_mul_f32 v[18:19], v[18:19], v[42:43] op_sel_hi:[1,0]
	v_pk_mul_f32 v[20:21], v[20:21], v[42:43] op_sel_hi:[1,0]
	v_pk_mul_f32 v[22:23], v[22:23], v[42:43] op_sel_hi:[1,0]
	v_pk_fma_f32 v[18:19], v[54:55], v[18:19], v[2:3]
	v_pk_fma_f32 v[16:17], v[52:53], v[16:17], v[0:1]
	v_pk_fma_f32 v[22:23], v[56:57], v[22:23], v[6:7]
	v_pk_fma_f32 v[20:21], v[50:51], v[20:21], v[4:5]
	v_cvt_pk_bf16_f32 v16, v16, v17
	v_cvt_pk_bf16_f32 v17, v18, v19
	v_cvt_pk_bf16_f32 v18, v20, v21
	v_cvt_pk_bf16_f32 v19, v22, v23
	global_store_dwordx2 v[40:41], v[16:17], off
	global_store_dwordx2 v[40:41], v[18:19], off offset:512
	v_pk_mul_f32 v[16:17], v[24:25], v[42:43] op_sel_hi:[1,0]
	v_pk_mul_f32 v[18:19], v[26:27], v[42:43] op_sel_hi:[1,0]
	v_pk_fma_f32 v[16:17], v[60:61], v[16:17], v[8:9]
	v_pk_fma_f32 v[18:19], v[62:63], v[18:19], v[10:11]
	v_cvt_pk_bf16_f32 v16, v16, v17
	v_cvt_pk_bf16_f32 v17, v18, v19
	global_store_dwordx2 v[40:41], v[16:17], off offset:1024
	v_pk_mul_f32 v[16:17], v[28:29], v[42:43] op_sel_hi:[1,0]
	v_pk_mul_f32 v[18:19], v[30:31], v[42:43] op_sel_hi:[1,0]
	v_pk_fma_f32 v[16:17], v[58:59], v[16:17], v[12:13]
	v_pk_fma_f32 v[18:19], v[64:65], v[18:19], v[14:15]
	v_cvt_pk_bf16_f32 v16, v16, v17
	v_cvt_pk_bf16_f32 v17, v18, v19
	global_store_dwordx2 v[40:41], v[16:17], off offset:1536
.LBB0_581:
	v_and_b32_e32 v17, 0xffff0000, v214
	v_and_b32_e32 v19, 0xffff0000, v215
	v_lshlrev_b32_e32 v16, 16, v214
	v_lshlrev_b32_e32 v18, 16, v215
	v_mul_f32_e32 v20, v19, v19
	v_and_b32_e32 v23, 0xffff0000, v213
	v_and_b32_e32 v22, 0xffff0000, v212
	v_and_b32_e32 v29, 0xffff0000, v208
	v_mul_f32_e32 v28, v17, v17
	v_pk_fma_f32 v[42:43], v[18:19], v[18:19], v[20:21] op_sel_hi:[1,1,0]
	v_lshlrev_b32_e32 v21, 16, v213
	v_lshlrev_b32_e32 v20, 16, v212
	v_pk_mul_f32 v[24:25], v[22:23], v[22:23]
	v_lshlrev_b32_e32 v31, 16, v208
	v_pk_fma_f32 v[46:47], v[16:17], v[16:17], v[28:29] op_sel_hi:[1,1,0]
	v_pk_fma_f32 v[44:45], v[20:21], v[20:21], v[24:25]
	v_mov_b32_e32 v30, v46
	v_mov_b32_e32 v48, v42
	v_mov_b32_e32 v49, v31
	v_and_b32_e32 v25, 0xffff0000, v210
	v_mul_f32_e32 v208, v29, v29
	v_pk_add_f32 v[42:43], v[46:47], v[42:43]
	v_pk_mul_f32 v[46:47], v[30:31], v[48:49]
	v_pk_add_f32 v[44:45], v[44:45], v[44:45] op_sel:[0,1] op_sel_hi:[1,0]
	v_lshlrev_b32_e32 v24, 16, v210
	v_and_b32_e32 v27, 0xffff0000, v211
	v_mov_b32_e32 v43, v47
	v_mov_b32_e32 v45, v208
	v_mul_f32_e32 v28, v25, v25
	v_lshlrev_b32_e32 v26, 16, v211
	v_lshlrev_b32_e32 v40, 16, v209
	v_and_b32_e32 v41, 0xffff0000, v209
	v_pk_add_f32 v[42:43], v[42:43], v[44:45]
	v_pk_fma_f32 v[44:45], v[24:25], v[24:25], v[28:29] op_sel_hi:[1,1,0]
	v_mul_f32_e32 v28, v27, v27
	v_mul_f32_e32 v209, v40, v40
	v_mul_f32_e32 v210, v41, v41
	v_pk_fma_f32 v[46:47], v[26:27], v[26:27], v[28:29] op_sel_hi:[1,1,0]
	v_mov_b32_e32 v45, v209
	v_mov_b32_e32 v47, v210
	v_pk_add_f32 v[44:45], v[44:45], v[46:47]
	v_lshlrev_b32_e32 v46, 16, v207
	v_pk_add_f32 v[42:43], v[42:43], v[44:45]
	v_lshlrev_b32_e32 v44, 16, v206
	v_add_f32_e32 v28, v42, v43
	s_nop 1
	v_mov_b32_dpp v30, v28 quad_perm:[1,0,3,2] row_mask:0xf bank_mask:0xf
	v_and_b32_e32 v45, 0xffff0000, v206
	v_and_b32_e32 v47, 0xffff0000, v207
	s_waitcnt lgkmcnt(0)
	v_add_f32_e32 v28, v28, v30
	s_nop 1
	v_mov_b32_dpp v30, v28 quad_perm:[2,3,0,1] row_mask:0xf bank_mask:0xf
	s_waitcnt lgkmcnt(0)
	v_add_f32_e32 v28, v28, v30
	s_nop 1
	v_mov_b32_dpp v30, v28 row_half_mirror row_mask:0xf bank_mask:0xf
	s_waitcnt lgkmcnt(0)
	v_add_f32_e32 v28, v28, v30
	s_nop 1
	v_mov_b32_dpp v30, v28 row_mirror row_mask:0xf bank_mask:0xf
	s_waitcnt lgkmcnt(0)
	v_add_f32_e32 v28, v28, v30
	s_waitcnt lgkmcnt(0)
	s_nop 0
	v_readlane_b32 s98, v28, 32
	v_readlane_b32 s100, v28, 48
	s_nop 1
	v_mov_b32_e32 v30, s100
	v_add_f32_e32 v30, s98, v30
	v_readlane_b32 s98, v28, 0
	v_readlane_b32 s100, v28, 16
	s_nop 1
	v_mov_b32_e32 v28, s100
	v_add_f32_e32 v28, s98, v28
	v_add_f32_e32 v28, v28, v30
	s_waitcnt lgkmcnt(0)
	v_fmamk_f32 v28, v28, 0x3a800000, v247
	v_mul_f32_e32 v30, 0x4b800000, v28
	v_cmp_gt_f32_e32 vcc, s35, v28
	s_nop 1
	v_cndmask_b32_e32 v28, v28, v30, vcc
	v_rsq_f32_e32 v28, v28
	s_nop 0
	v_mul_f32_e32 v30, 0x45800000, v28
	v_cndmask_b32_e32 v42, v28, v30, vcc
	v_pk_mul_f32 v[16:17], v[42:43], v[16:17] op_sel_hi:[0,1]
	v_pk_mul_f32 v[18:19], v[42:43], v[18:19] op_sel_hi:[0,1]
	v_pk_fma_f32 v[18:19], v[88:89], v[18:19], v[46:47]
	v_pk_fma_f32 v[16:17], v[86:87], v[16:17], v[44:45]
	s_and_b64 vcc, exec, s[6:7]
	v_lshl_add_u64 v[44:45], v[196:197], 2, s[0:1]
	s_cbranch_vccnz .LBB0_835
	global_store_dwordx4 v[44:45], v[16:19], off
	s_cbranch_execnz .LBB0_584

.LBB0_593:
	s_and_b64 vcc, exec, s[4:5]
	s_cbranch_vccnz .LBB0_595
	v_mul_f32_e32 v40, v17, v17
	v_mul_f32_e32 v41, v19, v19
	v_fmac_f32_e32 v40, v16, v16
	v_fmac_f32_e32 v41, v18, v18
	v_add_f32_e32 v40, v40, v41
	v_mul_f32_e32 v41, v21, v21
	v_mul_f32_e32 v42, v23, v23
	v_fmac_f32_e32 v41, v20, v20
	v_fmac_f32_e32 v42, v22, v22
	v_add_f32_e32 v41, v41, v42
	v_add_f32_e32 v40, v40, v41
	v_mul_f32_e32 v41, v25, v25
	v_mul_f32_e32 v42, v27, v27
	v_fmac_f32_e32 v41, v24, v24
	v_fmac_f32_e32 v42, v26, v26
	v_add_f32_e32 v41, v41, v42
	v_add_f32_e32 v40, v41, v40
	v_mul_f32_e32 v41, v29, v29
	v_mul_f32_e32 v42, v31, v31
	v_fmac_f32_e32 v41, v28, v28
	v_fmac_f32_e32 v42, v30, v30
	v_add_f32_e32 v41, v41, v42
	v_add_f32_e32 v40, v41, v40
	s_nop 1
	v_mov_b32_dpp v41, v40 quad_perm:[1,0,3,2] row_mask:0xf bank_mask:0xf
	s_waitcnt lgkmcnt(0)
	v_add_f32_e32 v40, v40, v41
	s_nop 1
	v_mov_b32_dpp v41, v40 quad_perm:[2,3,0,1] row_mask:0xf bank_mask:0xf
	s_waitcnt lgkmcnt(0)
	v_add_f32_e32 v40, v40, v41
	s_nop 1
	v_mov_b32_dpp v41, v40 row_half_mirror row_mask:0xf bank_mask:0xf
	s_waitcnt lgkmcnt(0)
	v_add_f32_e32 v40, v40, v41
	s_nop 1
	v_mov_b32_dpp v41, v40 row_mirror row_mask:0xf bank_mask:0xf
	s_waitcnt lgkmcnt(0)
	v_add_f32_e32 v40, v40, v41
	s_waitcnt lgkmcnt(0)
	s_nop 0
	v_readlane_b32 s98, v40, 32
	v_readlane_b32 s100, v40, 48
	s_nop 1
	v_mov_b32_e32 v41, s100
	v_add_f32_e32 v41, s98, v41
	v_readlane_b32 s98, v40, 0
	v_readlane_b32 s100, v40, 16
	s_nop 1
	v_mov_b32_e32 v40, s100
	v_add_f32_e32 v40, s98, v40
	v_add_f32_e32 v40, v40, v41
	s_waitcnt lgkmcnt(0)
	v_fmamk_f32 v40, v40, 0x3a800000, v247
	v_mul_f32_e32 v41, 0x4b800000, v40
	v_cmp_gt_f32_e32 vcc, s35, v40
	s_nop 1
	v_cndmask_b32_e32 v40, v40, v41, vcc
	v_rsq_f32_e32 v42, v40
	v_lshl_add_u64 v[40:41], v[196:197], 1, s[42:43]
	v_mul_f32_e32 v43, 0x45800000, v42
	v_cndmask_b32_e32 v42, v42, v43, vcc
	v_pk_mul_f32 v[16:17], v[16:17], v[42:43] op_sel_hi:[1,0]
	v_pk_mul_f32 v[18:19], v[18:19], v[42:43] op_sel_hi:[1,0]
	v_pk_mul_f32 v[20:21], v[20:21], v[42:43] op_sel_hi:[1,0]
	v_pk_mul_f32 v[22:23], v[22:23], v[42:43] op_sel_hi:[1,0]
	v_pk_fma_f32 v[18:19], v[54:55], v[18:19], v[2:3]
	v_pk_fma_f32 v[16:17], v[52:53], v[16:17], v[0:1]
	v_pk_fma_f32 v[22:23], v[56:57], v[22:23], v[6:7]
	v_pk_fma_f32 v[20:21], v[50:51], v[20:21], v[4:5]
	v_cvt_pk_bf16_f32 v16, v16, v17
	v_cvt_pk_bf16_f32 v17, v18, v19
	v_cvt_pk_bf16_f32 v18, v20, v21
	v_cvt_pk_bf16_f32 v19, v22, v23
	global_store_dwordx2 v[40:41], v[16:17], off
	global_store_dwordx2 v[40:41], v[18:19], off offset:512
	v_pk_mul_f32 v[16:17], v[24:25], v[42:43] op_sel_hi:[1,0]
	v_pk_mul_f32 v[18:19], v[26:27], v[42:43] op_sel_hi:[1,0]
	v_pk_fma_f32 v[16:17], v[60:61], v[16:17], v[8:9]
	v_pk_fma_f32 v[18:19], v[62:63], v[18:19], v[10:11]
	v_cvt_pk_bf16_f32 v16, v16, v17
	v_cvt_pk_bf16_f32 v17, v18, v19
	global_store_dwordx2 v[40:41], v[16:17], off offset:1024
	v_pk_mul_f32 v[16:17], v[28:29], v[42:43] op_sel_hi:[1,0]
	v_pk_mul_f32 v[18:19], v[30:31], v[42:43] op_sel_hi:[1,0]
	v_pk_fma_f32 v[16:17], v[58:59], v[16:17], v[12:13]
	v_pk_fma_f32 v[18:19], v[64:65], v[18:19], v[14:15]
	v_cvt_pk_bf16_f32 v16, v16, v17
	v_cvt_pk_bf16_f32 v17, v18, v19
	global_store_dwordx2 v[40:41], v[16:17], off offset:1536
.LBB0_595:
	v_and_b32_e32 v17, 0xffff0000, v194
	v_and_b32_e32 v19, 0xffff0000, v195
	v_lshlrev_b32_e32 v16, 16, v194
	v_lshlrev_b32_e32 v18, 16, v195
	v_mul_f32_e32 v20, v19, v19
	v_and_b32_e32 v23, 0xffff0000, v193
	v_and_b32_e32 v22, 0xffff0000, v192
	v_and_b32_e32 v29, 0xffff0000, v188
	v_mul_f32_e32 v28, v17, v17
	v_pk_fma_f32 v[42:43], v[18:19], v[18:19], v[20:21] op_sel_hi:[1,1,0]
	v_lshlrev_b32_e32 v21, 16, v193
	v_lshlrev_b32_e32 v20, 16, v192
	v_pk_mul_f32 v[24:25], v[22:23], v[22:23]
	v_lshlrev_b32_e32 v31, 16, v188
	v_pk_fma_f32 v[46:47], v[16:17], v[16:17], v[28:29] op_sel_hi:[1,1,0]
	v_pk_fma_f32 v[44:45], v[20:21], v[20:21], v[24:25]
	v_mov_b32_e32 v30, v46
	v_mov_b32_e32 v48, v42
	v_mov_b32_e32 v49, v31
	v_and_b32_e32 v25, 0xffff0000, v190
	v_mul_f32_e32 v188, v29, v29
	v_pk_add_f32 v[42:43], v[46:47], v[42:43]
	v_pk_mul_f32 v[46:47], v[30:31], v[48:49]
	v_pk_add_f32 v[44:45], v[44:45], v[44:45] op_sel:[0,1] op_sel_hi:[1,0]
	v_lshlrev_b32_e32 v24, 16, v190
	v_and_b32_e32 v27, 0xffff0000, v191
	v_mov_b32_e32 v43, v47
	v_mov_b32_e32 v45, v188
	v_mul_f32_e32 v28, v25, v25
	v_lshlrev_b32_e32 v26, 16, v191
	v_lshlrev_b32_e32 v40, 16, v189
	v_and_b32_e32 v41, 0xffff0000, v189
	v_pk_add_f32 v[42:43], v[42:43], v[44:45]
	v_pk_fma_f32 v[44:45], v[24:25], v[24:25], v[28:29] op_sel_hi:[1,1,0]
	v_mul_f32_e32 v28, v27, v27
	v_mul_f32_e32 v189, v40, v40
	v_mul_f32_e32 v190, v41, v41
	v_pk_fma_f32 v[46:47], v[26:27], v[26:27], v[28:29] op_sel_hi:[1,1,0]
	v_mov_b32_e32 v45, v189
	v_mov_b32_e32 v47, v190
	v_pk_add_f32 v[44:45], v[44:45], v[46:47]
	v_lshlrev_b32_e32 v46, 16, v187
	v_pk_add_f32 v[42:43], v[42:43], v[44:45]
	v_lshlrev_b32_e32 v44, 16, v186
	v_add_f32_e32 v28, v42, v43
	s_nop 1
	v_mov_b32_dpp v30, v28 quad_perm:[1,0,3,2] row_mask:0xf bank_mask:0xf
	v_and_b32_e32 v45, 0xffff0000, v186
	v_and_b32_e32 v47, 0xffff0000, v187
	s_waitcnt lgkmcnt(0)
	v_add_f32_e32 v28, v28, v30
	s_nop 1
	v_mov_b32_dpp v30, v28 quad_perm:[2,3,0,1] row_mask:0xf bank_mask:0xf
	s_waitcnt lgkmcnt(0)
	v_add_f32_e32 v28, v28, v30
	s_nop 1
	v_mov_b32_dpp v30, v28 row_half_mirror row_mask:0xf bank_mask:0xf
	s_waitcnt lgkmcnt(0)
	v_add_f32_e32 v28, v28, v30
	s_nop 1
	v_mov_b32_dpp v30, v28 row_mirror row_mask:0xf bank_mask:0xf
	s_waitcnt lgkmcnt(0)
	v_add_f32_e32 v28, v28, v30
	s_waitcnt lgkmcnt(0)
	s_nop 0
	v_readlane_b32 s98, v28, 32
	v_readlane_b32 s100, v28, 48
	s_nop 1
	v_mov_b32_e32 v30, s100
	v_add_f32_e32 v30, s98, v30
	v_readlane_b32 s98, v28, 0
	v_readlane_b32 s100, v28, 16
	s_nop 1
	v_mov_b32_e32 v28, s100
	v_add_f32_e32 v28, s98, v28
	v_add_f32_e32 v28, v28, v30
	s_waitcnt lgkmcnt(0)
	v_fmamk_f32 v28, v28, 0x3a800000, v247
	v_mul_f32_e32 v30, 0x4b800000, v28
	v_cmp_gt_f32_e32 vcc, s35, v28
	s_nop 1
	v_cndmask_b32_e32 v28, v28, v30, vcc
	v_rsq_f32_e32 v28, v28
	s_nop 0
	v_mul_f32_e32 v30, 0x45800000, v28
	v_cndmask_b32_e32 v42, v28, v30, vcc
	v_pk_mul_f32 v[16:17], v[42:43], v[16:17] op_sel_hi:[0,1]
	v_pk_mul_f32 v[18:19], v[42:43], v[18:19] op_sel_hi:[0,1]
	v_pk_fma_f32 v[18:19], v[88:89], v[18:19], v[46:47]
	v_pk_fma_f32 v[16:17], v[86:87], v[16:17], v[44:45]
	s_and_b64 vcc, exec, s[6:7]
	v_lshl_add_u64 v[44:45], v[176:177], 2, s[0:1]
	s_cbranch_vccnz .LBB0_839
	global_store_dwordx4 v[44:45], v[16:19], off
	s_cbranch_execnz .LBB0_598

.LBB0_607:
	s_and_b64 vcc, exec, s[4:5]
	s_cbranch_vccnz .LBB0_609
	v_mul_f32_e32 v40, v17, v17
	v_mul_f32_e32 v41, v19, v19
	v_fmac_f32_e32 v40, v16, v16
	v_fmac_f32_e32 v41, v18, v18
	v_add_f32_e32 v40, v40, v41
	v_mul_f32_e32 v41, v21, v21
	v_mul_f32_e32 v42, v23, v23
	v_fmac_f32_e32 v41, v20, v20
	v_fmac_f32_e32 v42, v22, v22
	v_add_f32_e32 v41, v41, v42
	v_add_f32_e32 v40, v40, v41
	v_mul_f32_e32 v41, v25, v25
	v_mul_f32_e32 v42, v27, v27
	v_fmac_f32_e32 v41, v24, v24
	v_fmac_f32_e32 v42, v26, v26
	v_add_f32_e32 v41, v41, v42
	v_add_f32_e32 v40, v41, v40
	v_mul_f32_e32 v41, v29, v29
	v_mul_f32_e32 v42, v31, v31
	v_fmac_f32_e32 v41, v28, v28
	v_fmac_f32_e32 v42, v30, v30
	v_add_f32_e32 v41, v41, v42
	v_add_f32_e32 v40, v41, v40
	s_nop 1
	v_mov_b32_dpp v41, v40 quad_perm:[1,0,3,2] row_mask:0xf bank_mask:0xf
	s_waitcnt lgkmcnt(0)
	v_add_f32_e32 v40, v40, v41
	s_nop 1
	v_mov_b32_dpp v41, v40 quad_perm:[2,3,0,1] row_mask:0xf bank_mask:0xf
	s_waitcnt lgkmcnt(0)
	v_add_f32_e32 v40, v40, v41
	s_nop 1
	v_mov_b32_dpp v41, v40 row_half_mirror row_mask:0xf bank_mask:0xf
	s_waitcnt lgkmcnt(0)
	v_add_f32_e32 v40, v40, v41
	s_nop 1
	v_mov_b32_dpp v41, v40 row_mirror row_mask:0xf bank_mask:0xf
	s_waitcnt lgkmcnt(0)
	v_add_f32_e32 v40, v40, v41
	s_waitcnt lgkmcnt(0)
	s_nop 0
	v_readlane_b32 s98, v40, 32
	v_readlane_b32 s100, v40, 48
	s_nop 1
	v_mov_b32_e32 v41, s100
	v_add_f32_e32 v41, s98, v41
	v_readlane_b32 s98, v40, 0
	v_readlane_b32 s100, v40, 16
	s_nop 1
	v_mov_b32_e32 v40, s100
	v_add_f32_e32 v40, s98, v40
	v_add_f32_e32 v40, v40, v41
	s_waitcnt lgkmcnt(0)
	v_fmamk_f32 v40, v40, 0x3a800000, v247
	v_mul_f32_e32 v41, 0x4b800000, v40
	v_cmp_gt_f32_e32 vcc, s35, v40
	s_nop 1
	v_cndmask_b32_e32 v40, v40, v41, vcc
	v_rsq_f32_e32 v42, v40
	v_lshl_add_u64 v[40:41], v[176:177], 1, s[42:43]
	v_mul_f32_e32 v43, 0x45800000, v42
	v_cndmask_b32_e32 v42, v42, v43, vcc
	v_pk_mul_f32 v[16:17], v[16:17], v[42:43] op_sel_hi:[1,0]
	v_pk_mul_f32 v[18:19], v[18:19], v[42:43] op_sel_hi:[1,0]
	v_pk_mul_f32 v[20:21], v[20:21], v[42:43] op_sel_hi:[1,0]
	v_pk_mul_f32 v[22:23], v[22:23], v[42:43] op_sel_hi:[1,0]
	v_pk_fma_f32 v[18:19], v[54:55], v[18:19], v[2:3]
	v_pk_fma_f32 v[16:17], v[52:53], v[16:17], v[0:1]
	v_pk_fma_f32 v[22:23], v[56:57], v[22:23], v[6:7]
	v_pk_fma_f32 v[20:21], v[50:51], v[20:21], v[4:5]
	v_cvt_pk_bf16_f32 v16, v16, v17
	v_cvt_pk_bf16_f32 v17, v18, v19
	v_cvt_pk_bf16_f32 v18, v20, v21
	v_cvt_pk_bf16_f32 v19, v22, v23
	global_store_dwordx2 v[40:41], v[16:17], off
	global_store_dwordx2 v[40:41], v[18:19], off offset:512
	v_pk_mul_f32 v[16:17], v[24:25], v[42:43] op_sel_hi:[1,0]
	v_pk_mul_f32 v[18:19], v[26:27], v[42:43] op_sel_hi:[1,0]
	v_pk_fma_f32 v[16:17], v[60:61], v[16:17], v[8:9]
	v_pk_fma_f32 v[18:19], v[62:63], v[18:19], v[10:11]
	v_cvt_pk_bf16_f32 v16, v16, v17
	v_cvt_pk_bf16_f32 v17, v18, v19
	global_store_dwordx2 v[40:41], v[16:17], off offset:1024
	v_pk_mul_f32 v[16:17], v[28:29], v[42:43] op_sel_hi:[1,0]
	v_pk_mul_f32 v[18:19], v[30:31], v[42:43] op_sel_hi:[1,0]
	v_pk_fma_f32 v[16:17], v[58:59], v[16:17], v[12:13]
	v_pk_fma_f32 v[18:19], v[64:65], v[18:19], v[14:15]
	v_cvt_pk_bf16_f32 v16, v16, v17
	v_cvt_pk_bf16_f32 v17, v18, v19
	global_store_dwordx2 v[40:41], v[16:17], off offset:1536
.LBB0_609:
	v_and_b32_e32 v17, 0xffff0000, v174
	v_and_b32_e32 v19, 0xffff0000, v175
	v_lshlrev_b32_e32 v16, 16, v174
	v_lshlrev_b32_e32 v18, 16, v175
	v_mul_f32_e32 v20, v19, v19
	v_and_b32_e32 v23, 0xffff0000, v173
	v_and_b32_e32 v22, 0xffff0000, v172
	v_and_b32_e32 v29, 0xffff0000, v168
	v_mul_f32_e32 v28, v17, v17
	v_pk_fma_f32 v[42:43], v[18:19], v[18:19], v[20:21] op_sel_hi:[1,1,0]
	v_lshlrev_b32_e32 v21, 16, v173
	v_lshlrev_b32_e32 v20, 16, v172
	v_pk_mul_f32 v[24:25], v[22:23], v[22:23]
	v_lshlrev_b32_e32 v31, 16, v168
	v_pk_fma_f32 v[46:47], v[16:17], v[16:17], v[28:29] op_sel_hi:[1,1,0]
	v_pk_fma_f32 v[44:45], v[20:21], v[20:21], v[24:25]
	v_mov_b32_e32 v30, v46
	v_mov_b32_e32 v48, v42
	v_mov_b32_e32 v49, v31
	v_and_b32_e32 v25, 0xffff0000, v170
	v_mul_f32_e32 v168, v29, v29
	v_pk_add_f32 v[42:43], v[46:47], v[42:43]
	v_pk_mul_f32 v[46:47], v[30:31], v[48:49]
	v_pk_add_f32 v[44:45], v[44:45], v[44:45] op_sel:[0,1] op_sel_hi:[1,0]
	v_lshlrev_b32_e32 v24, 16, v170
	v_and_b32_e32 v27, 0xffff0000, v171
	v_mov_b32_e32 v43, v47
	v_mov_b32_e32 v45, v168
	v_mul_f32_e32 v28, v25, v25
	v_lshlrev_b32_e32 v26, 16, v171
	v_lshlrev_b32_e32 v40, 16, v169
	v_and_b32_e32 v41, 0xffff0000, v169
	v_pk_add_f32 v[42:43], v[42:43], v[44:45]
	v_pk_fma_f32 v[44:45], v[24:25], v[24:25], v[28:29] op_sel_hi:[1,1,0]
	v_mul_f32_e32 v28, v27, v27
	v_mul_f32_e32 v169, v40, v40
	v_mul_f32_e32 v170, v41, v41
	v_pk_fma_f32 v[46:47], v[26:27], v[26:27], v[28:29] op_sel_hi:[1,1,0]
	v_mov_b32_e32 v45, v169
	v_mov_b32_e32 v47, v170
	v_pk_add_f32 v[44:45], v[44:45], v[46:47]
	v_lshlrev_b32_e32 v46, 16, v167
	v_pk_add_f32 v[42:43], v[42:43], v[44:45]
	v_lshlrev_b32_e32 v44, 16, v166
	v_add_f32_e32 v28, v42, v43
	s_nop 1
	v_mov_b32_dpp v30, v28 quad_perm:[1,0,3,2] row_mask:0xf bank_mask:0xf
	v_and_b32_e32 v45, 0xffff0000, v166
	v_and_b32_e32 v47, 0xffff0000, v167
	s_waitcnt lgkmcnt(0)
	v_add_f32_e32 v28, v28, v30
	s_nop 1
	v_mov_b32_dpp v30, v28 quad_perm:[2,3,0,1] row_mask:0xf bank_mask:0xf
	s_waitcnt lgkmcnt(0)
	v_add_f32_e32 v28, v28, v30
	s_nop 1
	v_mov_b32_dpp v30, v28 row_half_mirror row_mask:0xf bank_mask:0xf
	s_waitcnt lgkmcnt(0)
	v_add_f32_e32 v28, v28, v30
	s_nop 1
	v_mov_b32_dpp v30, v28 row_mirror row_mask:0xf bank_mask:0xf
	s_waitcnt lgkmcnt(0)
	v_add_f32_e32 v28, v28, v30
	s_waitcnt lgkmcnt(0)
	s_nop 0
	v_readlane_b32 s98, v28, 32
	v_readlane_b32 s100, v28, 48
	s_nop 1
	v_mov_b32_e32 v30, s100
	v_add_f32_e32 v30, s98, v30
	v_readlane_b32 s98, v28, 0
	v_readlane_b32 s100, v28, 16
	s_nop 1
	v_mov_b32_e32 v28, s100
	v_add_f32_e32 v28, s98, v28
	v_add_f32_e32 v28, v28, v30
	s_waitcnt lgkmcnt(0)
	v_fmamk_f32 v28, v28, 0x3a800000, v247
	v_mul_f32_e32 v30, 0x4b800000, v28
	v_cmp_gt_f32_e32 vcc, s35, v28
	s_nop 1
	v_cndmask_b32_e32 v28, v28, v30, vcc
	v_rsq_f32_e32 v28, v28
	s_nop 0
	v_mul_f32_e32 v30, 0x45800000, v28
	v_cndmask_b32_e32 v42, v28, v30, vcc
	v_pk_mul_f32 v[16:17], v[42:43], v[16:17] op_sel_hi:[0,1]
	v_pk_mul_f32 v[18:19], v[42:43], v[18:19] op_sel_hi:[0,1]
	v_pk_fma_f32 v[18:19], v[88:89], v[18:19], v[46:47]
	v_pk_fma_f32 v[16:17], v[86:87], v[16:17], v[44:45]
	s_and_b64 vcc, exec, s[6:7]
	v_lshl_add_u64 v[44:45], v[156:157], 2, s[0:1]
	s_cbranch_vccnz .LBB0_843
	global_store_dwordx4 v[44:45], v[16:19], off
	s_cbranch_execnz .LBB0_612

.LBB0_621:
	s_and_b64 vcc, exec, s[4:5]
	s_cbranch_vccnz .LBB0_623
	v_mul_f32_e32 v40, v17, v17
	v_mul_f32_e32 v41, v19, v19
	v_fmac_f32_e32 v40, v16, v16
	v_fmac_f32_e32 v41, v18, v18
	v_add_f32_e32 v40, v40, v41
	v_mul_f32_e32 v41, v21, v21
	v_mul_f32_e32 v42, v23, v23
	v_fmac_f32_e32 v41, v20, v20
	v_fmac_f32_e32 v42, v22, v22
	v_add_f32_e32 v41, v41, v42
	v_add_f32_e32 v40, v40, v41
	v_mul_f32_e32 v41, v25, v25
	v_mul_f32_e32 v42, v27, v27
	v_fmac_f32_e32 v41, v24, v24
	v_fmac_f32_e32 v42, v26, v26
	v_add_f32_e32 v41, v41, v42
	v_add_f32_e32 v40, v41, v40
	v_mul_f32_e32 v41, v29, v29
	v_mul_f32_e32 v42, v31, v31
	v_fmac_f32_e32 v41, v28, v28
	v_fmac_f32_e32 v42, v30, v30
	v_add_f32_e32 v41, v41, v42
	v_add_f32_e32 v40, v41, v40
	s_nop 1
	v_mov_b32_dpp v41, v40 quad_perm:[1,0,3,2] row_mask:0xf bank_mask:0xf
	s_waitcnt lgkmcnt(0)
	v_add_f32_e32 v40, v40, v41
	s_nop 1
	v_mov_b32_dpp v41, v40 quad_perm:[2,3,0,1] row_mask:0xf bank_mask:0xf
	s_waitcnt lgkmcnt(0)
	v_add_f32_e32 v40, v40, v41
	s_nop 1
	v_mov_b32_dpp v41, v40 row_half_mirror row_mask:0xf bank_mask:0xf
	s_waitcnt lgkmcnt(0)
	v_add_f32_e32 v40, v40, v41
	s_nop 1
	v_mov_b32_dpp v41, v40 row_mirror row_mask:0xf bank_mask:0xf
	s_waitcnt lgkmcnt(0)
	v_add_f32_e32 v40, v40, v41
	s_waitcnt lgkmcnt(0)
	s_nop 0
	v_readlane_b32 s98, v40, 32
	v_readlane_b32 s100, v40, 48
	s_nop 1
	v_mov_b32_e32 v41, s100
	v_add_f32_e32 v41, s98, v41
	v_readlane_b32 s98, v40, 0
	v_readlane_b32 s100, v40, 16
	s_nop 1
	v_mov_b32_e32 v40, s100
	v_add_f32_e32 v40, s98, v40
	v_add_f32_e32 v40, v40, v41
	s_waitcnt lgkmcnt(0)
	v_fmamk_f32 v40, v40, 0x3a800000, v247
	v_mul_f32_e32 v41, 0x4b800000, v40
	v_cmp_gt_f32_e32 vcc, s35, v40
	s_nop 1
	v_cndmask_b32_e32 v40, v40, v41, vcc
	v_rsq_f32_e32 v42, v40
	v_lshl_add_u64 v[40:41], v[156:157], 1, s[42:43]
	v_mul_f32_e32 v43, 0x45800000, v42
	v_cndmask_b32_e32 v42, v42, v43, vcc
	v_pk_mul_f32 v[16:17], v[16:17], v[42:43] op_sel_hi:[1,0]
	v_pk_mul_f32 v[18:19], v[18:19], v[42:43] op_sel_hi:[1,0]
	v_pk_mul_f32 v[20:21], v[20:21], v[42:43] op_sel_hi:[1,0]
	v_pk_mul_f32 v[22:23], v[22:23], v[42:43] op_sel_hi:[1,0]
	v_pk_fma_f32 v[18:19], v[54:55], v[18:19], v[2:3]
	v_pk_fma_f32 v[16:17], v[52:53], v[16:17], v[0:1]
	v_pk_fma_f32 v[22:23], v[56:57], v[22:23], v[6:7]
	v_pk_fma_f32 v[20:21], v[50:51], v[20:21], v[4:5]
	v_cvt_pk_bf16_f32 v16, v16, v17
	v_cvt_pk_bf16_f32 v17, v18, v19
	v_cvt_pk_bf16_f32 v18, v20, v21
	v_cvt_pk_bf16_f32 v19, v22, v23
	global_store_dwordx2 v[40:41], v[16:17], off
	global_store_dwordx2 v[40:41], v[18:19], off offset:512
	v_pk_mul_f32 v[16:17], v[24:25], v[42:43] op_sel_hi:[1,0]
	v_pk_mul_f32 v[18:19], v[26:27], v[42:43] op_sel_hi:[1,0]
	v_pk_fma_f32 v[16:17], v[60:61], v[16:17], v[8:9]
	v_pk_fma_f32 v[18:19], v[62:63], v[18:19], v[10:11]
	v_cvt_pk_bf16_f32 v16, v16, v17
	v_cvt_pk_bf16_f32 v17, v18, v19
	global_store_dwordx2 v[40:41], v[16:17], off offset:1024
	v_pk_mul_f32 v[16:17], v[28:29], v[42:43] op_sel_hi:[1,0]
	v_pk_mul_f32 v[18:19], v[30:31], v[42:43] op_sel_hi:[1,0]
	v_pk_fma_f32 v[16:17], v[58:59], v[16:17], v[12:13]
	v_pk_fma_f32 v[18:19], v[64:65], v[18:19], v[14:15]
	v_cvt_pk_bf16_f32 v16, v16, v17
	v_cvt_pk_bf16_f32 v17, v18, v19
	global_store_dwordx2 v[40:41], v[16:17], off offset:1536
.LBB0_623:
	v_and_b32_e32 v17, 0xffff0000, v154
	v_and_b32_e32 v19, 0xffff0000, v155
	v_lshlrev_b32_e32 v16, 16, v154
	v_lshlrev_b32_e32 v18, 16, v155
	v_mul_f32_e32 v20, v19, v19
	v_and_b32_e32 v23, 0xffff0000, v153
	v_and_b32_e32 v22, 0xffff0000, v152
	v_and_b32_e32 v29, 0xffff0000, v148
	v_mul_f32_e32 v28, v17, v17
	v_pk_fma_f32 v[42:43], v[18:19], v[18:19], v[20:21] op_sel_hi:[1,1,0]
	v_lshlrev_b32_e32 v21, 16, v153
	v_lshlrev_b32_e32 v20, 16, v152
	v_pk_mul_f32 v[24:25], v[22:23], v[22:23]
	v_lshlrev_b32_e32 v31, 16, v148
	v_pk_fma_f32 v[46:47], v[16:17], v[16:17], v[28:29] op_sel_hi:[1,1,0]
	v_pk_fma_f32 v[44:45], v[20:21], v[20:21], v[24:25]
	v_mov_b32_e32 v30, v46
	v_mov_b32_e32 v48, v42
	v_mov_b32_e32 v49, v31
	v_and_b32_e32 v25, 0xffff0000, v150
	v_mul_f32_e32 v148, v29, v29
	v_pk_add_f32 v[42:43], v[46:47], v[42:43]
	v_pk_mul_f32 v[46:47], v[30:31], v[48:49]
	v_pk_add_f32 v[44:45], v[44:45], v[44:45] op_sel:[0,1] op_sel_hi:[1,0]
	v_lshlrev_b32_e32 v24, 16, v150
	v_and_b32_e32 v27, 0xffff0000, v151
	v_mov_b32_e32 v43, v47
	v_mov_b32_e32 v45, v148
	v_mul_f32_e32 v28, v25, v25
	v_lshlrev_b32_e32 v26, 16, v151
	v_lshlrev_b32_e32 v40, 16, v149
	v_and_b32_e32 v41, 0xffff0000, v149
	v_pk_add_f32 v[42:43], v[42:43], v[44:45]
	v_pk_fma_f32 v[44:45], v[24:25], v[24:25], v[28:29] op_sel_hi:[1,1,0]
	v_mul_f32_e32 v28, v27, v27
	v_mul_f32_e32 v149, v40, v40
	v_mul_f32_e32 v150, v41, v41
	v_pk_fma_f32 v[46:47], v[26:27], v[26:27], v[28:29] op_sel_hi:[1,1,0]
	v_mov_b32_e32 v45, v149
	v_mov_b32_e32 v47, v150
	v_pk_add_f32 v[44:45], v[44:45], v[46:47]
	v_lshlrev_b32_e32 v46, 16, v147
	v_pk_add_f32 v[42:43], v[42:43], v[44:45]
	v_lshlrev_b32_e32 v44, 16, v146
	v_add_f32_e32 v28, v42, v43
	s_nop 1
	v_mov_b32_dpp v30, v28 quad_perm:[1,0,3,2] row_mask:0xf bank_mask:0xf
	v_and_b32_e32 v45, 0xffff0000, v146
	v_and_b32_e32 v47, 0xffff0000, v147
	s_waitcnt lgkmcnt(0)
	v_add_f32_e32 v28, v28, v30
	s_nop 1
	v_mov_b32_dpp v30, v28 quad_perm:[2,3,0,1] row_mask:0xf bank_mask:0xf
	s_waitcnt lgkmcnt(0)
	v_add_f32_e32 v28, v28, v30
	s_nop 1
	v_mov_b32_dpp v30, v28 row_half_mirror row_mask:0xf bank_mask:0xf
	s_waitcnt lgkmcnt(0)
	v_add_f32_e32 v28, v28, v30
	s_nop 1
	v_mov_b32_dpp v30, v28 row_mirror row_mask:0xf bank_mask:0xf
	s_waitcnt lgkmcnt(0)
	v_add_f32_e32 v28, v28, v30
	s_waitcnt lgkmcnt(0)
	s_nop 0
	v_readlane_b32 s98, v28, 32
	v_readlane_b32 s100, v28, 48
	s_nop 1
	v_mov_b32_e32 v30, s100
	v_add_f32_e32 v30, s98, v30
	v_readlane_b32 s98, v28, 0
	v_readlane_b32 s100, v28, 16
	s_nop 1
	v_mov_b32_e32 v28, s100
	v_add_f32_e32 v28, s98, v28
	v_add_f32_e32 v28, v28, v30
	s_waitcnt lgkmcnt(0)
	v_fmamk_f32 v28, v28, 0x3a800000, v247
	v_mul_f32_e32 v30, 0x4b800000, v28
	v_cmp_gt_f32_e32 vcc, s35, v28
	s_nop 1
	v_cndmask_b32_e32 v28, v28, v30, vcc
	v_rsq_f32_e32 v28, v28
	s_nop 0
	v_mul_f32_e32 v30, 0x45800000, v28
	v_cndmask_b32_e32 v42, v28, v30, vcc
	v_pk_mul_f32 v[16:17], v[42:43], v[16:17] op_sel_hi:[0,1]
	v_pk_mul_f32 v[18:19], v[42:43], v[18:19] op_sel_hi:[0,1]
	v_pk_fma_f32 v[18:19], v[88:89], v[18:19], v[46:47]
	v_pk_fma_f32 v[16:17], v[86:87], v[16:17], v[44:45]
	s_and_b64 vcc, exec, s[6:7]
	v_lshl_add_u64 v[44:45], v[134:135], 2, s[0:1]
	s_cbranch_vccnz .LBB0_847
	global_store_dwordx4 v[44:45], v[16:19], off
	s_cbranch_execnz .LBB0_626

.LBB0_635:
	s_and_b64 vcc, exec, s[4:5]
	s_cbranch_vccnz .LBB0_637
	v_mul_f32_e32 v40, v17, v17
	v_mul_f32_e32 v41, v19, v19
	v_fmac_f32_e32 v40, v16, v16
	v_fmac_f32_e32 v41, v18, v18
	v_add_f32_e32 v40, v40, v41
	v_mul_f32_e32 v41, v21, v21
	v_mul_f32_e32 v42, v23, v23
	v_fmac_f32_e32 v41, v20, v20
	v_fmac_f32_e32 v42, v22, v22
	v_add_f32_e32 v41, v41, v42
	v_add_f32_e32 v40, v40, v41
	v_mul_f32_e32 v41, v25, v25
	v_mul_f32_e32 v42, v27, v27
	v_fmac_f32_e32 v41, v24, v24
	v_fmac_f32_e32 v42, v26, v26
	v_add_f32_e32 v41, v41, v42
	v_add_f32_e32 v40, v41, v40
	v_mul_f32_e32 v41, v29, v29
	v_mul_f32_e32 v42, v31, v31
	v_fmac_f32_e32 v41, v28, v28
	v_fmac_f32_e32 v42, v30, v30
	v_add_f32_e32 v41, v41, v42
	v_add_f32_e32 v40, v41, v40
	s_nop 1
	v_mov_b32_dpp v41, v40 quad_perm:[1,0,3,2] row_mask:0xf bank_mask:0xf
	s_waitcnt lgkmcnt(0)
	v_add_f32_e32 v40, v40, v41
	s_nop 1
	v_mov_b32_dpp v41, v40 quad_perm:[2,3,0,1] row_mask:0xf bank_mask:0xf
	s_waitcnt lgkmcnt(0)
	v_add_f32_e32 v40, v40, v41
	s_nop 1
	v_mov_b32_dpp v41, v40 row_half_mirror row_mask:0xf bank_mask:0xf
	s_waitcnt lgkmcnt(0)
	v_add_f32_e32 v40, v40, v41
	s_nop 1
	v_mov_b32_dpp v41, v40 row_mirror row_mask:0xf bank_mask:0xf
	s_waitcnt lgkmcnt(0)
	v_add_f32_e32 v40, v40, v41
	s_waitcnt lgkmcnt(0)
	s_nop 0
	v_readlane_b32 s98, v40, 32
	v_readlane_b32 s100, v40, 48
	s_nop 1
	v_mov_b32_e32 v41, s100
	v_add_f32_e32 v41, s98, v41
	v_readlane_b32 s98, v40, 0
	v_readlane_b32 s100, v40, 16
	s_nop 1
	v_mov_b32_e32 v40, s100
	v_add_f32_e32 v40, s98, v40
	v_add_f32_e32 v40, v40, v41
	s_waitcnt lgkmcnt(0)
	v_fmamk_f32 v40, v40, 0x3a800000, v247
	v_mul_f32_e32 v41, 0x4b800000, v40
	v_cmp_gt_f32_e32 vcc, s35, v40
	s_nop 1
	v_cndmask_b32_e32 v40, v40, v41, vcc
	v_rsq_f32_e32 v42, v40
	v_lshl_add_u64 v[40:41], v[134:135], 1, s[42:43]
	v_mul_f32_e32 v43, 0x45800000, v42
	v_cndmask_b32_e32 v42, v42, v43, vcc
	v_pk_mul_f32 v[16:17], v[16:17], v[42:43] op_sel_hi:[1,0]
	v_pk_mul_f32 v[18:19], v[18:19], v[42:43] op_sel_hi:[1,0]
	v_pk_mul_f32 v[20:21], v[20:21], v[42:43] op_sel_hi:[1,0]
	v_pk_mul_f32 v[22:23], v[22:23], v[42:43] op_sel_hi:[1,0]
	v_pk_fma_f32 v[18:19], v[54:55], v[18:19], v[2:3]
	v_pk_fma_f32 v[16:17], v[52:53], v[16:17], v[0:1]
	v_pk_fma_f32 v[22:23], v[56:57], v[22:23], v[6:7]
	v_pk_fma_f32 v[20:21], v[50:51], v[20:21], v[4:5]
	v_cvt_pk_bf16_f32 v16, v16, v17
	v_cvt_pk_bf16_f32 v17, v18, v19
	v_cvt_pk_bf16_f32 v18, v20, v21
	v_cvt_pk_bf16_f32 v19, v22, v23
	global_store_dwordx2 v[40:41], v[16:17], off
	global_store_dwordx2 v[40:41], v[18:19], off offset:512
	v_pk_mul_f32 v[16:17], v[24:25], v[42:43] op_sel_hi:[1,0]
	v_pk_mul_f32 v[18:19], v[26:27], v[42:43] op_sel_hi:[1,0]
	v_pk_fma_f32 v[16:17], v[60:61], v[16:17], v[8:9]
	v_pk_fma_f32 v[18:19], v[62:63], v[18:19], v[10:11]
	v_cvt_pk_bf16_f32 v16, v16, v17
	v_cvt_pk_bf16_f32 v17, v18, v19
	global_store_dwordx2 v[40:41], v[16:17], off offset:1024
	v_pk_mul_f32 v[16:17], v[28:29], v[42:43] op_sel_hi:[1,0]
	v_pk_mul_f32 v[18:19], v[30:31], v[42:43] op_sel_hi:[1,0]
	v_pk_fma_f32 v[16:17], v[58:59], v[16:17], v[12:13]
	v_pk_fma_f32 v[18:19], v[64:65], v[18:19], v[14:15]
	v_cvt_pk_bf16_f32 v16, v16, v17
	v_cvt_pk_bf16_f32 v17, v18, v19
	global_store_dwordx2 v[40:41], v[16:17], off offset:1536
.LBB0_637:
	v_and_b32_e32 v17, 0xffff0000, v132
	v_and_b32_e32 v19, 0xffff0000, v133
	v_lshlrev_b32_e32 v16, 16, v132
	v_lshlrev_b32_e32 v18, 16, v133
	v_mul_f32_e32 v20, v19, v19
	v_and_b32_e32 v23, 0xffff0000, v131
	v_and_b32_e32 v22, 0xffff0000, v130
	v_and_b32_e32 v29, 0xffff0000, v126
	v_mul_f32_e32 v28, v17, v17
	v_pk_fma_f32 v[42:43], v[18:19], v[18:19], v[20:21] op_sel_hi:[1,1,0]
	v_lshlrev_b32_e32 v21, 16, v131
	v_lshlrev_b32_e32 v20, 16, v130
	v_pk_mul_f32 v[24:25], v[22:23], v[22:23]
	v_lshlrev_b32_e32 v31, 16, v126
	v_pk_fma_f32 v[46:47], v[16:17], v[16:17], v[28:29] op_sel_hi:[1,1,0]
	v_pk_fma_f32 v[44:45], v[20:21], v[20:21], v[24:25]
	v_mov_b32_e32 v30, v46
	v_mov_b32_e32 v48, v42
	v_mov_b32_e32 v49, v31
	v_and_b32_e32 v25, 0xffff0000, v128
	v_mul_f32_e32 v126, v29, v29
	v_pk_add_f32 v[42:43], v[46:47], v[42:43]
	v_pk_mul_f32 v[46:47], v[30:31], v[48:49]
	v_pk_add_f32 v[44:45], v[44:45], v[44:45] op_sel:[0,1] op_sel_hi:[1,0]
	v_lshlrev_b32_e32 v24, 16, v128
	v_and_b32_e32 v27, 0xffff0000, v129
	v_mov_b32_e32 v43, v47
	v_mov_b32_e32 v45, v126
	v_mul_f32_e32 v28, v25, v25
	v_lshlrev_b32_e32 v26, 16, v129
	v_lshlrev_b32_e32 v40, 16, v127
	v_and_b32_e32 v41, 0xffff0000, v127
	v_pk_add_f32 v[42:43], v[42:43], v[44:45]
	v_pk_fma_f32 v[44:45], v[24:25], v[24:25], v[28:29] op_sel_hi:[1,1,0]
	v_mul_f32_e32 v28, v27, v27
	v_mul_f32_e32 v127, v40, v40
	v_mul_f32_e32 v128, v41, v41
	v_pk_fma_f32 v[46:47], v[26:27], v[26:27], v[28:29] op_sel_hi:[1,1,0]
	v_mov_b32_e32 v45, v127
	v_mov_b32_e32 v47, v128
	v_pk_add_f32 v[44:45], v[44:45], v[46:47]
	v_lshlrev_b32_e32 v46, 16, v125
	v_pk_add_f32 v[42:43], v[42:43], v[44:45]
	v_lshlrev_b32_e32 v44, 16, v124
	v_add_f32_e32 v28, v42, v43
	s_nop 1
	v_mov_b32_dpp v30, v28 quad_perm:[1,0,3,2] row_mask:0xf bank_mask:0xf
	v_and_b32_e32 v45, 0xffff0000, v124
	v_and_b32_e32 v47, 0xffff0000, v125
	s_waitcnt lgkmcnt(0)
	v_add_f32_e32 v28, v28, v30
	s_nop 1
	v_mov_b32_dpp v30, v28 quad_perm:[2,3,0,1] row_mask:0xf bank_mask:0xf
	s_waitcnt lgkmcnt(0)
	v_add_f32_e32 v28, v28, v30
	s_nop 1
	v_mov_b32_dpp v30, v28 row_half_mirror row_mask:0xf bank_mask:0xf
	s_waitcnt lgkmcnt(0)
	v_add_f32_e32 v28, v28, v30
	s_nop 1
	v_mov_b32_dpp v30, v28 row_mirror row_mask:0xf bank_mask:0xf
	s_waitcnt lgkmcnt(0)
	v_add_f32_e32 v28, v28, v30
	s_waitcnt lgkmcnt(0)
	s_nop 0
	v_readlane_b32 s98, v28, 32
	v_readlane_b32 s100, v28, 48
	s_nop 1
	v_mov_b32_e32 v30, s100
	v_add_f32_e32 v30, s98, v30
	v_readlane_b32 s98, v28, 0
	v_readlane_b32 s100, v28, 16
	s_nop 1
	v_mov_b32_e32 v28, s100
	v_add_f32_e32 v28, s98, v28
	v_add_f32_e32 v28, v28, v30
	s_waitcnt lgkmcnt(0)
	v_fmamk_f32 v28, v28, 0x3a800000, v247
	v_mul_f32_e32 v30, 0x4b800000, v28
	v_cmp_gt_f32_e32 vcc, s35, v28
	s_nop 1
	v_cndmask_b32_e32 v28, v28, v30, vcc
	v_rsq_f32_e32 v28, v28
	s_nop 0
	v_mul_f32_e32 v30, 0x45800000, v28
	v_cndmask_b32_e32 v42, v28, v30, vcc
	v_pk_mul_f32 v[16:17], v[42:43], v[16:17] op_sel_hi:[0,1]
	v_pk_mul_f32 v[18:19], v[42:43], v[18:19] op_sel_hi:[0,1]
	v_pk_fma_f32 v[18:19], v[88:89], v[18:19], v[46:47]
	v_pk_fma_f32 v[16:17], v[86:87], v[16:17], v[44:45]
	s_and_b64 vcc, exec, s[6:7]
	v_lshl_add_u64 v[44:45], v[114:115], 2, s[0:1]
	s_cbranch_vccnz .LBB0_851
	global_store_dwordx4 v[44:45], v[16:19], off
	s_cbranch_execnz .LBB0_640

.LBB0_649:
	s_and_b64 vcc, exec, s[4:5]
	s_cbranch_vccnz .LBB0_651
	v_mul_f32_e32 v40, v17, v17
	v_mul_f32_e32 v41, v19, v19
	v_fmac_f32_e32 v40, v16, v16
	v_fmac_f32_e32 v41, v18, v18
	v_add_f32_e32 v40, v40, v41
	v_mul_f32_e32 v41, v21, v21
	v_mul_f32_e32 v42, v23, v23
	v_fmac_f32_e32 v41, v20, v20
	v_fmac_f32_e32 v42, v22, v22
	v_add_f32_e32 v41, v41, v42
	v_add_f32_e32 v40, v40, v41
	v_mul_f32_e32 v41, v25, v25
	v_mul_f32_e32 v42, v27, v27
	v_fmac_f32_e32 v41, v24, v24
	v_fmac_f32_e32 v42, v26, v26
	v_add_f32_e32 v41, v41, v42
	v_add_f32_e32 v40, v41, v40
	v_mul_f32_e32 v41, v29, v29
	v_mul_f32_e32 v42, v31, v31
	v_fmac_f32_e32 v41, v28, v28
	v_fmac_f32_e32 v42, v30, v30
	v_add_f32_e32 v41, v41, v42
	v_add_f32_e32 v40, v41, v40
	s_nop 1
	v_mov_b32_dpp v41, v40 quad_perm:[1,0,3,2] row_mask:0xf bank_mask:0xf
	s_waitcnt lgkmcnt(0)
	v_add_f32_e32 v40, v40, v41
	s_nop 1
	v_mov_b32_dpp v41, v40 quad_perm:[2,3,0,1] row_mask:0xf bank_mask:0xf
	s_waitcnt lgkmcnt(0)
	v_add_f32_e32 v40, v40, v41
	s_nop 1
	v_mov_b32_dpp v41, v40 row_half_mirror row_mask:0xf bank_mask:0xf
	s_waitcnt lgkmcnt(0)
	v_add_f32_e32 v40, v40, v41
	s_nop 1
	v_mov_b32_dpp v41, v40 row_mirror row_mask:0xf bank_mask:0xf
	s_waitcnt lgkmcnt(0)
	v_add_f32_e32 v40, v40, v41
	s_waitcnt lgkmcnt(0)
	s_nop 0
	v_readlane_b32 s98, v40, 32
	v_readlane_b32 s100, v40, 48
	s_nop 1
	v_mov_b32_e32 v41, s100
	v_add_f32_e32 v41, s98, v41
	v_readlane_b32 s98, v40, 0
	v_readlane_b32 s100, v40, 16
	s_nop 1
	v_mov_b32_e32 v40, s100
	v_add_f32_e32 v40, s98, v40
	v_add_f32_e32 v40, v40, v41
	s_waitcnt lgkmcnt(0)
	v_fmamk_f32 v40, v40, 0x3a800000, v247
	v_mul_f32_e32 v41, 0x4b800000, v40
	v_cmp_gt_f32_e32 vcc, s35, v40
	s_nop 1
	v_cndmask_b32_e32 v40, v40, v41, vcc
	v_rsq_f32_e32 v42, v40
	v_lshl_add_u64 v[40:41], v[114:115], 1, s[42:43]
	v_mul_f32_e32 v43, 0x45800000, v42
	v_cndmask_b32_e32 v42, v42, v43, vcc
	v_pk_mul_f32 v[16:17], v[16:17], v[42:43] op_sel_hi:[1,0]
	v_pk_mul_f32 v[18:19], v[18:19], v[42:43] op_sel_hi:[1,0]
	v_pk_mul_f32 v[20:21], v[20:21], v[42:43] op_sel_hi:[1,0]
	v_pk_mul_f32 v[22:23], v[22:23], v[42:43] op_sel_hi:[1,0]
	v_pk_fma_f32 v[18:19], v[54:55], v[18:19], v[2:3]
	v_pk_fma_f32 v[16:17], v[52:53], v[16:17], v[0:1]
	v_pk_fma_f32 v[22:23], v[56:57], v[22:23], v[6:7]
	v_pk_fma_f32 v[20:21], v[50:51], v[20:21], v[4:5]
	v_cvt_pk_bf16_f32 v16, v16, v17
	v_cvt_pk_bf16_f32 v17, v18, v19
	v_cvt_pk_bf16_f32 v18, v20, v21
	v_cvt_pk_bf16_f32 v19, v22, v23
	global_store_dwordx2 v[40:41], v[16:17], off
	global_store_dwordx2 v[40:41], v[18:19], off offset:512
	v_pk_mul_f32 v[16:17], v[24:25], v[42:43] op_sel_hi:[1,0]
	v_pk_mul_f32 v[18:19], v[26:27], v[42:43] op_sel_hi:[1,0]
	v_pk_fma_f32 v[16:17], v[60:61], v[16:17], v[8:9]
	v_pk_fma_f32 v[18:19], v[62:63], v[18:19], v[10:11]
	v_cvt_pk_bf16_f32 v16, v16, v17
	v_cvt_pk_bf16_f32 v17, v18, v19
	global_store_dwordx2 v[40:41], v[16:17], off offset:1024
	v_pk_mul_f32 v[16:17], v[28:29], v[42:43] op_sel_hi:[1,0]
	v_pk_mul_f32 v[18:19], v[30:31], v[42:43] op_sel_hi:[1,0]
	v_pk_fma_f32 v[16:17], v[58:59], v[16:17], v[12:13]
	v_pk_fma_f32 v[18:19], v[64:65], v[18:19], v[14:15]
	v_cvt_pk_bf16_f32 v16, v16, v17
	v_cvt_pk_bf16_f32 v17, v18, v19
	global_store_dwordx2 v[40:41], v[16:17], off offset:1536
.LBB0_651:
	v_and_b32_e32 v17, 0xffff0000, v112
	v_and_b32_e32 v19, 0xffff0000, v113
	v_lshlrev_b32_e32 v16, 16, v112
	v_lshlrev_b32_e32 v18, 16, v113
	v_mul_f32_e32 v20, v19, v19
	v_and_b32_e32 v23, 0xffff0000, v111
	v_and_b32_e32 v22, 0xffff0000, v110
	v_and_b32_e32 v29, 0xffff0000, v106
	v_mul_f32_e32 v28, v17, v17
	v_pk_fma_f32 v[42:43], v[18:19], v[18:19], v[20:21] op_sel_hi:[1,1,0]
	v_lshlrev_b32_e32 v21, 16, v111
	v_lshlrev_b32_e32 v20, 16, v110
	v_pk_mul_f32 v[24:25], v[22:23], v[22:23]
	v_lshlrev_b32_e32 v31, 16, v106
	v_pk_fma_f32 v[46:47], v[16:17], v[16:17], v[28:29] op_sel_hi:[1,1,0]
	v_pk_fma_f32 v[44:45], v[20:21], v[20:21], v[24:25]
	v_mov_b32_e32 v30, v46
	v_mov_b32_e32 v48, v42
	v_mov_b32_e32 v49, v31
	v_and_b32_e32 v25, 0xffff0000, v108
	v_mul_f32_e32 v106, v29, v29
	v_pk_add_f32 v[42:43], v[46:47], v[42:43]
	v_pk_mul_f32 v[46:47], v[30:31], v[48:49]
	v_pk_add_f32 v[44:45], v[44:45], v[44:45] op_sel:[0,1] op_sel_hi:[1,0]
	v_lshlrev_b32_e32 v24, 16, v108
	v_and_b32_e32 v27, 0xffff0000, v109
	v_mov_b32_e32 v43, v47
	v_mov_b32_e32 v45, v106
	v_mul_f32_e32 v28, v25, v25
	v_lshlrev_b32_e32 v26, 16, v109
	v_lshlrev_b32_e32 v40, 16, v107
	v_and_b32_e32 v41, 0xffff0000, v107
	v_pk_add_f32 v[42:43], v[42:43], v[44:45]
	v_pk_fma_f32 v[44:45], v[24:25], v[24:25], v[28:29] op_sel_hi:[1,1,0]
	v_mul_f32_e32 v28, v27, v27
	v_mul_f32_e32 v107, v40, v40
	v_mul_f32_e32 v108, v41, v41
	v_pk_fma_f32 v[46:47], v[26:27], v[26:27], v[28:29] op_sel_hi:[1,1,0]
	v_mov_b32_e32 v45, v107
	v_mov_b32_e32 v47, v108
	v_pk_add_f32 v[44:45], v[44:45], v[46:47]
	v_lshlrev_b32_e32 v46, 16, v105
	v_pk_add_f32 v[42:43], v[42:43], v[44:45]
	v_lshlrev_b32_e32 v44, 16, v104
	v_add_f32_e32 v28, v42, v43
	s_nop 1
	v_mov_b32_dpp v30, v28 quad_perm:[1,0,3,2] row_mask:0xf bank_mask:0xf
	v_and_b32_e32 v45, 0xffff0000, v104
	v_and_b32_e32 v47, 0xffff0000, v105
	s_waitcnt lgkmcnt(0)
	v_add_f32_e32 v28, v28, v30
	s_nop 1
	v_mov_b32_dpp v30, v28 quad_perm:[2,3,0,1] row_mask:0xf bank_mask:0xf
	s_waitcnt lgkmcnt(0)
	v_add_f32_e32 v28, v28, v30
	s_nop 1
	v_mov_b32_dpp v30, v28 row_half_mirror row_mask:0xf bank_mask:0xf
	s_waitcnt lgkmcnt(0)
	v_add_f32_e32 v28, v28, v30
	s_nop 1
	v_mov_b32_dpp v30, v28 row_mirror row_mask:0xf bank_mask:0xf
	s_waitcnt lgkmcnt(0)
	v_add_f32_e32 v28, v28, v30
	s_waitcnt lgkmcnt(0)
	s_nop 0
	v_readlane_b32 s98, v28, 32
	v_readlane_b32 s100, v28, 48
	s_nop 1
	v_mov_b32_e32 v30, s100
	v_add_f32_e32 v30, s98, v30
	v_readlane_b32 s98, v28, 0
	v_readlane_b32 s100, v28, 16
	s_nop 1
	v_mov_b32_e32 v28, s100
	v_add_f32_e32 v28, s98, v28
	v_add_f32_e32 v28, v28, v30
	s_waitcnt lgkmcnt(0)
	v_fmamk_f32 v28, v28, 0x3a800000, v247
	v_mul_f32_e32 v30, 0x4b800000, v28
	v_cmp_gt_f32_e32 vcc, s35, v28
	s_nop 1
	v_cndmask_b32_e32 v28, v28, v30, vcc
	v_rsq_f32_e32 v28, v28
	s_nop 0
	v_mul_f32_e32 v30, 0x45800000, v28
	v_cndmask_b32_e32 v42, v28, v30, vcc
	v_pk_mul_f32 v[16:17], v[42:43], v[16:17] op_sel_hi:[0,1]
	v_pk_mul_f32 v[18:19], v[42:43], v[18:19] op_sel_hi:[0,1]
	v_pk_fma_f32 v[18:19], v[88:89], v[18:19], v[46:47]
	v_pk_fma_f32 v[16:17], v[86:87], v[16:17], v[44:45]
	s_and_b64 vcc, exec, s[6:7]
	v_lshl_add_u64 v[44:45], v[94:95], 2, s[0:1]
	s_cbranch_vccnz .LBB0_855
	global_store_dwordx4 v[44:45], v[16:19], off
	s_cbranch_execnz .LBB0_654

.LBB0_663:
	s_and_b64 vcc, exec, s[4:5]
	s_cbranch_vccnz .LBB0_665
	v_mul_f32_e32 v40, v17, v17
	v_mul_f32_e32 v41, v19, v19
	v_fmac_f32_e32 v40, v16, v16
	v_fmac_f32_e32 v41, v18, v18
	v_add_f32_e32 v40, v40, v41
	v_mul_f32_e32 v41, v21, v21
	v_mul_f32_e32 v42, v23, v23
	v_fmac_f32_e32 v41, v20, v20
	v_fmac_f32_e32 v42, v22, v22
	v_add_f32_e32 v41, v41, v42
	v_add_f32_e32 v40, v40, v41
	v_mul_f32_e32 v41, v25, v25
	v_mul_f32_e32 v42, v27, v27
	v_fmac_f32_e32 v41, v24, v24
	v_fmac_f32_e32 v42, v26, v26
	v_add_f32_e32 v41, v41, v42
	v_add_f32_e32 v40, v41, v40
	v_mul_f32_e32 v41, v29, v29
	v_mul_f32_e32 v42, v31, v31
	v_fmac_f32_e32 v41, v28, v28
	v_fmac_f32_e32 v42, v30, v30
	v_add_f32_e32 v41, v41, v42
	v_add_f32_e32 v40, v41, v40
	s_nop 1
	v_mov_b32_dpp v41, v40 quad_perm:[1,0,3,2] row_mask:0xf bank_mask:0xf
	s_waitcnt lgkmcnt(0)
	v_add_f32_e32 v40, v40, v41
	s_nop 1
	v_mov_b32_dpp v41, v40 quad_perm:[2,3,0,1] row_mask:0xf bank_mask:0xf
	s_waitcnt lgkmcnt(0)
	v_add_f32_e32 v40, v40, v41
	s_nop 1
	v_mov_b32_dpp v41, v40 row_half_mirror row_mask:0xf bank_mask:0xf
	s_waitcnt lgkmcnt(0)
	v_add_f32_e32 v40, v40, v41
	s_nop 1
	v_mov_b32_dpp v41, v40 row_mirror row_mask:0xf bank_mask:0xf
	s_waitcnt lgkmcnt(0)
	v_add_f32_e32 v40, v40, v41
	s_waitcnt lgkmcnt(0)
	s_nop 0
	v_readlane_b32 s98, v40, 32
	v_readlane_b32 s100, v40, 48
	s_nop 1
	v_mov_b32_e32 v41, s100
	v_add_f32_e32 v41, s98, v41
	v_readlane_b32 s98, v40, 0
	v_readlane_b32 s100, v40, 16
	s_nop 1
	v_mov_b32_e32 v40, s100
	v_add_f32_e32 v40, s98, v40
	v_add_f32_e32 v40, v40, v41
	s_waitcnt lgkmcnt(0)
	v_fmamk_f32 v40, v40, 0x3a800000, v247
	v_mul_f32_e32 v41, 0x4b800000, v40
	v_cmp_gt_f32_e32 vcc, s35, v40
	s_nop 1
	v_cndmask_b32_e32 v40, v40, v41, vcc
	v_rsq_f32_e32 v42, v40
	v_lshl_add_u64 v[40:41], v[94:95], 1, s[42:43]
	v_mul_f32_e32 v43, 0x45800000, v42
	v_cndmask_b32_e32 v42, v42, v43, vcc
	v_pk_mul_f32 v[16:17], v[16:17], v[42:43] op_sel_hi:[1,0]
	v_pk_mul_f32 v[18:19], v[18:19], v[42:43] op_sel_hi:[1,0]
	v_pk_mul_f32 v[20:21], v[20:21], v[42:43] op_sel_hi:[1,0]
	v_pk_mul_f32 v[22:23], v[22:23], v[42:43] op_sel_hi:[1,0]
	v_pk_fma_f32 v[18:19], v[54:55], v[18:19], v[2:3]
	v_pk_fma_f32 v[16:17], v[52:53], v[16:17], v[0:1]
	v_pk_fma_f32 v[22:23], v[56:57], v[22:23], v[6:7]
	v_pk_fma_f32 v[20:21], v[50:51], v[20:21], v[4:5]
	v_cvt_pk_bf16_f32 v16, v16, v17
	v_cvt_pk_bf16_f32 v17, v18, v19
	v_cvt_pk_bf16_f32 v18, v20, v21
	v_cvt_pk_bf16_f32 v19, v22, v23
	global_store_dwordx2 v[40:41], v[16:17], off
	global_store_dwordx2 v[40:41], v[18:19], off offset:512
	v_pk_mul_f32 v[16:17], v[24:25], v[42:43] op_sel_hi:[1,0]
	v_pk_mul_f32 v[18:19], v[26:27], v[42:43] op_sel_hi:[1,0]
	v_pk_fma_f32 v[16:17], v[60:61], v[16:17], v[8:9]
	v_pk_fma_f32 v[18:19], v[62:63], v[18:19], v[10:11]
	v_cvt_pk_bf16_f32 v16, v16, v17
	v_cvt_pk_bf16_f32 v17, v18, v19
	global_store_dwordx2 v[40:41], v[16:17], off offset:1024
	v_pk_mul_f32 v[16:17], v[28:29], v[42:43] op_sel_hi:[1,0]
	v_pk_mul_f32 v[18:19], v[30:31], v[42:43] op_sel_hi:[1,0]
	v_pk_fma_f32 v[16:17], v[58:59], v[16:17], v[12:13]
	v_pk_fma_f32 v[18:19], v[64:65], v[18:19], v[14:15]
	v_cvt_pk_bf16_f32 v16, v16, v17
	v_cvt_pk_bf16_f32 v17, v18, v19
	global_store_dwordx2 v[40:41], v[16:17], off offset:1536
.LBB0_665:
	v_and_b32_e32 v17, 0xffff0000, v84
	v_and_b32_e32 v19, 0xffff0000, v85
	v_lshlrev_b32_e32 v16, 16, v84
	v_lshlrev_b32_e32 v18, 16, v85
	v_mul_f32_e32 v20, v19, v19
	v_and_b32_e32 v23, 0xffff0000, v83
	v_and_b32_e32 v22, 0xffff0000, v82
	v_and_b32_e32 v29, 0xffff0000, v78
	v_mul_f32_e32 v28, v17, v17
	v_pk_fma_f32 v[42:43], v[18:19], v[18:19], v[20:21] op_sel_hi:[1,1,0]
	v_lshlrev_b32_e32 v21, 16, v83
	v_lshlrev_b32_e32 v20, 16, v82
	v_pk_mul_f32 v[24:25], v[22:23], v[22:23]
	v_lshlrev_b32_e32 v31, 16, v78
	v_pk_fma_f32 v[46:47], v[16:17], v[16:17], v[28:29] op_sel_hi:[1,1,0]
	v_pk_fma_f32 v[44:45], v[20:21], v[20:21], v[24:25]
	v_mov_b32_e32 v30, v46
	v_mov_b32_e32 v48, v42
	v_mov_b32_e32 v49, v31
	v_and_b32_e32 v25, 0xffff0000, v80
	v_mul_f32_e32 v78, v29, v29
	v_pk_add_f32 v[42:43], v[46:47], v[42:43]
	v_pk_mul_f32 v[46:47], v[30:31], v[48:49]
	v_pk_add_f32 v[44:45], v[44:45], v[44:45] op_sel:[0,1] op_sel_hi:[1,0]
	v_lshlrev_b32_e32 v24, 16, v80
	v_and_b32_e32 v27, 0xffff0000, v81
	v_mov_b32_e32 v43, v47
	v_mov_b32_e32 v45, v78
	v_mul_f32_e32 v28, v25, v25
	v_lshlrev_b32_e32 v26, 16, v81
	v_lshlrev_b32_e32 v40, 16, v79
	v_and_b32_e32 v41, 0xffff0000, v79
	v_pk_add_f32 v[42:43], v[42:43], v[44:45]
	v_pk_fma_f32 v[44:45], v[24:25], v[24:25], v[28:29] op_sel_hi:[1,1,0]
	v_mul_f32_e32 v28, v27, v27
	v_mul_f32_e32 v79, v40, v40
	v_mul_f32_e32 v80, v41, v41
	v_pk_fma_f32 v[46:47], v[26:27], v[26:27], v[28:29] op_sel_hi:[1,1,0]
	v_mov_b32_e32 v45, v79
	v_mov_b32_e32 v47, v80
	v_pk_add_f32 v[44:45], v[44:45], v[46:47]
	v_lshlrev_b32_e32 v46, 16, v77
	v_pk_add_f32 v[42:43], v[42:43], v[44:45]
	v_lshlrev_b32_e32 v44, 16, v76
	v_add_f32_e32 v28, v42, v43
	s_nop 1
	v_mov_b32_dpp v30, v28 quad_perm:[1,0,3,2] row_mask:0xf bank_mask:0xf
	v_and_b32_e32 v45, 0xffff0000, v76
	v_and_b32_e32 v47, 0xffff0000, v77
	s_waitcnt lgkmcnt(0)
	v_add_f32_e32 v28, v28, v30
	s_nop 1
	v_mov_b32_dpp v30, v28 quad_perm:[2,3,0,1] row_mask:0xf bank_mask:0xf
	s_waitcnt lgkmcnt(0)
	v_add_f32_e32 v28, v28, v30
	s_nop 1
	v_mov_b32_dpp v30, v28 row_half_mirror row_mask:0xf bank_mask:0xf
	s_waitcnt lgkmcnt(0)
	v_add_f32_e32 v28, v28, v30
	s_nop 1
	v_mov_b32_dpp v30, v28 row_mirror row_mask:0xf bank_mask:0xf
	s_waitcnt lgkmcnt(0)
	v_add_f32_e32 v28, v28, v30
	s_waitcnt lgkmcnt(0)
	s_nop 0
	v_readlane_b32 s98, v28, 32
	v_readlane_b32 s100, v28, 48
	s_nop 1
	v_mov_b32_e32 v30, s100
	v_add_f32_e32 v30, s98, v30
	v_readlane_b32 s98, v28, 0
	v_readlane_b32 s100, v28, 16
	s_nop 1
	v_mov_b32_e32 v28, s100
	v_add_f32_e32 v28, s98, v28
	v_add_f32_e32 v28, v28, v30
	s_waitcnt lgkmcnt(0)
	v_fmamk_f32 v28, v28, 0x3a800000, v247
	v_mul_f32_e32 v30, 0x4b800000, v28
	v_cmp_gt_f32_e32 vcc, s35, v28
	s_nop 1
	v_cndmask_b32_e32 v28, v28, v30, vcc
	v_rsq_f32_e32 v28, v28
	s_nop 0
	v_mul_f32_e32 v30, 0x45800000, v28
	v_cndmask_b32_e32 v42, v28, v30, vcc
	v_pk_mul_f32 v[16:17], v[42:43], v[16:17] op_sel_hi:[0,1]
	v_pk_mul_f32 v[18:19], v[42:43], v[18:19] op_sel_hi:[0,1]
	v_pk_fma_f32 v[18:19], v[88:89], v[18:19], v[46:47]
	v_pk_fma_f32 v[16:17], v[86:87], v[16:17], v[44:45]
	s_and_b64 vcc, exec, s[6:7]
	v_lshl_add_u64 v[44:45], v[66:67], 2, s[0:1]
	s_cbranch_vccnz .LBB0_859
	global_store_dwordx4 v[44:45], v[16:19], off
	s_cbranch_execnz .LBB0_668

.LBB0_677:
	s_and_b64 vcc, exec, s[4:5]
	s_cbranch_vccnz .LBB0_679
	v_mul_f32_e32 v32, v17, v17
	v_mul_f32_e32 v33, v19, v19
	v_fmac_f32_e32 v32, v16, v16
	v_fmac_f32_e32 v33, v18, v18
	v_add_f32_e32 v32, v32, v33
	v_mul_f32_e32 v33, v21, v21
	v_mul_f32_e32 v34, v23, v23
	v_fmac_f32_e32 v33, v20, v20
	v_fmac_f32_e32 v34, v22, v22
	v_add_f32_e32 v33, v33, v34
	v_add_f32_e32 v32, v32, v33
	v_mul_f32_e32 v33, v25, v25
	v_mul_f32_e32 v34, v27, v27
	v_fmac_f32_e32 v33, v24, v24
	v_fmac_f32_e32 v34, v26, v26
	v_add_f32_e32 v33, v33, v34
	v_add_f32_e32 v32, v33, v32
	v_mul_f32_e32 v33, v29, v29
	v_mul_f32_e32 v34, v31, v31
	v_fmac_f32_e32 v33, v28, v28
	v_fmac_f32_e32 v34, v30, v30
	v_add_f32_e32 v33, v33, v34
	v_add_f32_e32 v32, v33, v32
	s_nop 1
	v_mov_b32_dpp v33, v32 quad_perm:[1,0,3,2] row_mask:0xf bank_mask:0xf
	s_mov_b64 s[4:5], 0
	s_waitcnt lgkmcnt(0)
	v_add_f32_e32 v32, v32, v33
	s_nop 1
	v_mov_b32_dpp v33, v32 quad_perm:[2,3,0,1] row_mask:0xf bank_mask:0xf
	s_waitcnt lgkmcnt(0)
	v_add_f32_e32 v32, v32, v33
	s_nop 1
	v_mov_b32_dpp v33, v32 row_half_mirror row_mask:0xf bank_mask:0xf
	s_waitcnt lgkmcnt(0)
	v_add_f32_e32 v32, v32, v33
	s_nop 1
	v_mov_b32_dpp v33, v32 row_mirror row_mask:0xf bank_mask:0xf
	s_waitcnt lgkmcnt(0)
	v_add_f32_e32 v32, v32, v33
	s_waitcnt lgkmcnt(0)
	s_nop 0
	v_readlane_b32 s98, v32, 32
	v_readlane_b32 s100, v32, 48
	s_nop 1
	v_mov_b32_e32 v33, s100
	v_add_f32_e32 v33, s98, v33
	v_readlane_b32 s98, v32, 0
	v_readlane_b32 s100, v32, 16
	s_nop 1
	v_mov_b32_e32 v32, s100
	v_add_f32_e32 v32, s98, v32
	v_add_f32_e32 v32, v32, v33
	s_waitcnt lgkmcnt(0)
	v_fmamk_f32 v32, v32, 0x3a800000, v247
	v_mul_f32_e32 v33, 0x4b800000, v32
	v_cmp_gt_f32_e32 vcc, s35, v32
	s_nop 1
	v_cndmask_b32_e32 v32, v32, v33, vcc
	v_rsq_f32_e32 v34, v32
	v_lshl_add_u64 v[32:33], v[66:67], 1, s[42:43]
	v_mul_f32_e32 v35, 0x45800000, v34
	v_cndmask_b32_e32 v34, v34, v35, vcc
	v_pk_mul_f32 v[16:17], v[16:17], v[34:35] op_sel_hi:[1,0]
	v_pk_mul_f32 v[18:19], v[18:19], v[34:35] op_sel_hi:[1,0]
	v_pk_mul_f32 v[20:21], v[20:21], v[34:35] op_sel_hi:[1,0]
	v_pk_mul_f32 v[22:23], v[22:23], v[34:35] op_sel_hi:[1,0]
	v_pk_fma_f32 v[2:3], v[54:55], v[18:19], v[2:3]
	v_pk_fma_f32 v[0:1], v[52:53], v[16:17], v[0:1]
	v_pk_fma_f32 v[6:7], v[56:57], v[22:23], v[6:7]
	v_pk_fma_f32 v[4:5], v[50:51], v[20:21], v[4:5]
	v_cvt_pk_bf16_f32 v0, v0, v1
	v_cvt_pk_bf16_f32 v1, v2, v3
	v_cvt_pk_bf16_f32 v2, v4, v5
	v_cvt_pk_bf16_f32 v3, v6, v7
	global_store_dwordx2 v[32:33], v[0:1], off
	global_store_dwordx2 v[32:33], v[2:3], off offset:512
	v_pk_mul_f32 v[0:1], v[24:25], v[34:35] op_sel_hi:[1,0]
	v_pk_mul_f32 v[2:3], v[26:27], v[34:35] op_sel_hi:[1,0]
	v_pk_fma_f32 v[0:1], v[60:61], v[0:1], v[8:9]
	v_pk_fma_f32 v[2:3], v[62:63], v[2:3], v[10:11]
	v_cvt_pk_bf16_f32 v0, v0, v1
	v_cvt_pk_bf16_f32 v1, v2, v3
	global_store_dwordx2 v[32:33], v[0:1], off offset:1024
	v_pk_mul_f32 v[0:1], v[28:29], v[34:35] op_sel_hi:[1,0]
	v_pk_mul_f32 v[2:3], v[30:31], v[34:35] op_sel_hi:[1,0]
	v_pk_fma_f32 v[0:1], v[58:59], v[0:1], v[12:13]
	v_pk_fma_f32 v[2:3], v[64:65], v[2:3], v[14:15]
	v_cvt_pk_bf16_f32 v0, v0, v1
	v_cvt_pk_bf16_f32 v1, v2, v3
	global_store_dwordx2 v[32:33], v[0:1], off offset:1536
	s_branch .LBB0_680
